# K-loop: barrier B moved 1 MFMA earlier in each MFMA segment
# speedup vs baseline: 1.1046x; 1.0015x over previous
.LBB0_390:
	s_add_u32 s38, s42, 0x100
	s_addc_u32 s39, s43, 0
	s_add_i32 s4, 0, 0x10000
	s_cmp_eq_u32 s73, 12
	s_cselect_b32 s69, s29, s39
	s_cselect_b32 s68, vcc_lo, s38
	s_cselect_b32 s67, s37, s72
	s_cselect_b32 s66, vcc_hi, s59
	s_add_i32 s6, 0, 0x14000
	v_add_u32_e32 v142, s4, v251
	v_add_u32_e32 v158, s6, v251
	ds_read_b128 v[130:133], v142
	ds_read_b128 v[134:137], v142 offset:1024
	ds_read_b128 v[138:141], v142 offset:2048
	ds_read_b128 v[142:145], v142 offset:3072
	ds_read_b128 v[146:149], v158
	ds_read_b128 v[150:153], v158 offset:1024
	ds_read_b128 v[154:157], v158 offset:2048
	ds_read_b128 v[158:161], v158 offset:3072
	v_lshl_add_u64 v[194:195], s[42:43], 0, v[228:229]
	s_add_i32 m0, s75, 0xc000
	ds_read_b128 v[162:165], v244
	ds_read_b128 v[166:169], v244 offset:1024
	ds_read_b128 v[170:173], v244 offset:2048
	ds_read_b128 v[174:177], v244 offset:3072
	ds_read_b128 v[178:181], v244 offset:4096
	ds_read_b128 v[182:185], v244 offset:5120
	ds_read_b128 v[186:189], v244 offset:6144
	ds_read_b128 v[190:193], v244 offset:7168
	global_load_lds_dwordx4 v[194:195], off
	v_lshl_add_u64 v[194:195], s[42:43], 0, v[230:231]
	s_add_i32 m0, s75, 0xe000
	s_nop 0
	global_load_lds_dwordx4 v[194:195], off
	s_waitcnt vmcnt(8)
	s_waitcnt lgkmcnt(0)
	s_barrier
	s_setprio 1
	s_waitcnt lgkmcnt(0)
	v_mfma_f32_16x16x32_bf16 v[114:117], v[130:133], v[162:165], v[114:117]
	v_mfma_f32_16x16x32_bf16 v[122:125], v[138:141], v[162:165], v[122:125]
	v_mfma_f32_16x16x32_bf16 v[118:121], v[130:133], v[170:173], v[118:121]
	v_mfma_f32_16x16x32_bf16 v[126:129], v[138:141], v[170:173], v[126:129]
	v_mfma_f32_16x16x32_bf16 v[54:57], v[130:133], v[178:181], v[54:57]
	v_mfma_f32_16x16x32_bf16 v[70:73], v[138:141], v[178:181], v[70:73]
	v_mfma_f32_16x16x32_bf16 v[50:53], v[130:133], v[186:189], v[50:53]
	v_mfma_f32_16x16x32_bf16 v[66:69], v[138:141], v[186:189], v[66:69]
	v_mfma_f32_16x16x32_bf16 v[114:117], v[134:137], v[166:169], v[114:117]
	v_mfma_f32_16x16x32_bf16 v[122:125], v[142:145], v[166:169], v[122:125]
	v_mfma_f32_16x16x32_bf16 v[118:121], v[134:137], v[174:177], v[118:121]
	v_mfma_f32_16x16x32_bf16 v[126:129], v[142:145], v[174:177], v[126:129]
	v_mfma_f32_16x16x32_bf16 v[54:57], v[134:137], v[182:185], v[54:57]
	v_mfma_f32_16x16x32_bf16 v[70:73], v[142:145], v[182:185], v[70:73]
	v_mfma_f32_16x16x32_bf16 v[50:53], v[134:137], v[190:193], v[50:53]
	v_mfma_f32_16x16x32_bf16 v[66:69], v[142:145], v[190:193], v[66:69]
	s_setprio 0
	s_setprio 1
	v_mfma_f32_16x16x32_bf16 v[106:109], v[146:149], v[162:165], v[106:109]
	v_mfma_f32_16x16x32_bf16 v[42:45], v[154:157], v[162:165], v[42:45]
	v_mfma_f32_16x16x32_bf16 v[110:113], v[146:149], v[170:173], v[110:113]
	v_mfma_f32_16x16x32_bf16 v[46:49], v[154:157], v[170:173], v[46:49]
	v_mfma_f32_16x16x32_bf16 v[30:33], v[146:149], v[178:181], v[30:33]
	v_mfma_f32_16x16x32_bf16 v[14:17], v[154:157], v[178:181], v[14:17]
	v_mfma_f32_16x16x32_bf16 v[26:29], v[146:149], v[186:189], v[26:29]
	v_mfma_f32_16x16x32_bf16 v[10:13], v[154:157], v[186:189], v[10:13]
	v_mfma_f32_16x16x32_bf16 v[106:109], v[150:153], v[166:169], v[106:109]
	v_mfma_f32_16x16x32_bf16 v[42:45], v[158:161], v[166:169], v[42:45]
	v_mfma_f32_16x16x32_bf16 v[110:113], v[150:153], v[174:177], v[110:113]
	v_mfma_f32_16x16x32_bf16 v[46:49], v[158:161], v[174:177], v[46:49]
	v_mfma_f32_16x16x32_bf16 v[30:33], v[150:153], v[182:185], v[30:33]
	v_mfma_f32_16x16x32_bf16 v[14:17], v[158:161], v[182:185], v[14:17]
	v_mfma_f32_16x16x32_bf16 v[26:29], v[150:153], v[190:193], v[26:29]
	s_barrier
	v_mfma_f32_16x16x32_bf16 v[10:13], v[158:161], v[190:193], v[10:13]
	s_setprio 0
	s_add_i32 s4, s4, s74
	v_lshl_add_u64 v[194:195], s[66:67], 0, v[0:1]
	s_mov_b32 m0, s4
	ds_read_b128 v[162:165], v244 offset:16384
	ds_read_b128 v[166:169], v244 offset:17408
	ds_read_b128 v[170:173], v244 offset:18432
	ds_read_b128 v[174:177], v244 offset:19456
	ds_read_b128 v[178:181], v244 offset:20480
	ds_read_b128 v[182:185], v244 offset:21504
	ds_read_b128 v[186:189], v244 offset:22528
	ds_read_b128 v[190:193], v244 offset:23552
	global_load_lds_dwordx4 v[194:195], off
	s_add_i32 m0, s4, 0x2000
	s_add_u32 s4, s66, 0x40000
	v_lshl_add_u64 v[196:197], s[66:67], 0, v[224:225]
	s_addc_u32 s5, s67, 0
	s_add_i32 s6, s6, s74
	global_load_lds_dwordx4 v[196:197], off
	v_lshl_add_u64 v[198:199], s[4:5], 0, v[0:1]
	s_mov_b32 m0, s6
	v_lshl_add_u64 v[200:201], s[68:69], 0, v[222:223]
	global_load_lds_dwordx4 v[198:199], off
	v_lshl_add_u64 v[198:199], s[4:5], 0, v[224:225]
	s_add_i32 m0, s6, 0x2000
	s_nop 0
	global_load_lds_dwordx4 v[198:199], off
	v_lshl_add_u64 v[198:199], s[68:69], 0, v[226:227]
	s_mov_b32 m0, s75
	s_nop 0
	global_load_lds_dwordx4 v[198:199], off
	s_mov_b32 m0, s76
	s_nop 0
	global_load_lds_dwordx4 v[200:201], off
	s_waitcnt vmcnt(8)
	s_waitcnt lgkmcnt(0)
	s_barrier
	s_setprio 1
	s_waitcnt lgkmcnt(0)
	v_mfma_f32_16x16x32_bf16 v[38:41], v[130:133], v[162:165], v[38:41]
	v_mfma_f32_16x16x32_bf16 v[62:65], v[138:141], v[162:165], v[62:65]
	v_mfma_f32_16x16x32_bf16 v[34:37], v[130:133], v[170:173], v[34:37]
	v_mfma_f32_16x16x32_bf16 v[58:61], v[138:141], v[170:173], v[58:61]
	v_mfma_f32_16x16x32_bf16 v[102:105], v[130:133], v[178:181], v[102:105]
	v_mfma_f32_16x16x32_bf16 v[98:101], v[138:141], v[178:181], v[98:101]
	v_mfma_f32_16x16x32_bf16 v[94:97], v[130:133], v[186:189], v[94:97]
	v_mfma_f32_16x16x32_bf16 v[90:93], v[138:141], v[186:189], v[90:93]
	v_mfma_f32_16x16x32_bf16 v[38:41], v[134:137], v[166:169], v[38:41]
	v_mfma_f32_16x16x32_bf16 v[62:65], v[142:145], v[166:169], v[62:65]
	v_mfma_f32_16x16x32_bf16 v[34:37], v[134:137], v[174:177], v[34:37]
	v_mfma_f32_16x16x32_bf16 v[58:61], v[142:145], v[174:177], v[58:61]
	v_mfma_f32_16x16x32_bf16 v[102:105], v[134:137], v[182:185], v[102:105]
	v_mfma_f32_16x16x32_bf16 v[98:101], v[142:145], v[182:185], v[98:101]
	v_mfma_f32_16x16x32_bf16 v[94:97], v[134:137], v[190:193], v[94:97]
	v_mfma_f32_16x16x32_bf16 v[90:93], v[142:145], v[190:193], v[90:93]
	s_setprio 0
	s_setprio 1
	v_mfma_f32_16x16x32_bf16 v[22:25], v[146:149], v[162:165], v[22:25]
	v_mfma_f32_16x16x32_bf16 v[6:9], v[154:157], v[162:165], v[6:9]
	v_mfma_f32_16x16x32_bf16 v[18:21], v[146:149], v[170:173], v[18:21]
	v_mfma_f32_16x16x32_bf16 v[2:5], v[154:157], v[170:173], v[2:5]
	v_mfma_f32_16x16x32_bf16 v[86:89], v[146:149], v[178:181], v[86:89]
	v_mfma_f32_16x16x32_bf16 v[82:85], v[154:157], v[178:181], v[82:85]
	v_mfma_f32_16x16x32_bf16 v[78:81], v[146:149], v[186:189], v[78:81]
	v_mfma_f32_16x16x32_bf16 v[74:77], v[154:157], v[186:189], v[74:77]
	v_mfma_f32_16x16x32_bf16 v[22:25], v[150:153], v[166:169], v[22:25]
	v_mfma_f32_16x16x32_bf16 v[6:9], v[158:161], v[166:169], v[6:9]
	v_mfma_f32_16x16x32_bf16 v[18:21], v[150:153], v[174:177], v[18:21]
	v_mfma_f32_16x16x32_bf16 v[2:5], v[158:161], v[174:177], v[2:5]
	v_mfma_f32_16x16x32_bf16 v[86:89], v[150:153], v[182:185], v[86:89]
	v_mfma_f32_16x16x32_bf16 v[82:85], v[158:161], v[182:185], v[82:85]
	v_mfma_f32_16x16x32_bf16 v[78:81], v[150:153], v[190:193], v[78:81]
	s_barrier
	v_mfma_f32_16x16x32_bf16 v[74:77], v[158:161], v[190:193], v[74:77]
	s_setprio 0
	s_add_i32 s6, 0, 0x18000
	s_add_i32 s7, 0, 0x1c000
	v_add_u32_e32 v142, s6, v251
	v_add_u32_e32 v158, s7, v251
	ds_read_b128 v[130:133], v142
	ds_read_b128 v[134:137], v142 offset:1024
	ds_read_b128 v[138:141], v142 offset:2048
	ds_read_b128 v[142:145], v142 offset:3072
	ds_read_b128 v[146:149], v158
	ds_read_b128 v[150:153], v158 offset:1024
	ds_read_b128 v[154:157], v158 offset:2048
	ds_read_b128 v[158:161], v158 offset:3072
	s_add_u32 s4, s68, 0x2000
	s_addc_u32 s5, s69, 0
	s_mov_b32 m0, s77
	v_lshl_add_u64 v[202:203], s[4:5], 0, v[226:227]
	ds_read_b128 v[162:165], v244 offset:32768
	ds_read_b128 v[166:169], v244 offset:33792
	ds_read_b128 v[170:173], v244 offset:34816
	ds_read_b128 v[174:177], v244 offset:35840
	ds_read_b128 v[178:181], v244 offset:36864
	ds_read_b128 v[182:185], v244 offset:37888
	ds_read_b128 v[186:189], v244 offset:38912
	ds_read_b128 v[190:193], v244 offset:39936
	global_load_lds_dwordx4 v[202:203], off
	v_lshl_add_u64 v[202:203], s[4:5], 0, v[222:223]
	s_mov_b32 m0, s78
	s_nop 0
	global_load_lds_dwordx4 v[202:203], off
	s_waitcnt vmcnt(8)
	s_waitcnt lgkmcnt(0)
	s_barrier
	s_setprio 1
	s_waitcnt lgkmcnt(0)
	v_mfma_f32_16x16x32_bf16 v[114:117], v[130:133], v[162:165], v[114:117]
	v_mfma_f32_16x16x32_bf16 v[122:125], v[138:141], v[162:165], v[122:125]
	v_mfma_f32_16x16x32_bf16 v[118:121], v[130:133], v[170:173], v[118:121]
	v_mfma_f32_16x16x32_bf16 v[126:129], v[138:141], v[170:173], v[126:129]
	v_mfma_f32_16x16x32_bf16 v[54:57], v[130:133], v[178:181], v[54:57]
	v_mfma_f32_16x16x32_bf16 v[70:73], v[138:141], v[178:181], v[70:73]
	v_mfma_f32_16x16x32_bf16 v[50:53], v[130:133], v[186:189], v[50:53]
	v_mfma_f32_16x16x32_bf16 v[66:69], v[138:141], v[186:189], v[66:69]
	v_mfma_f32_16x16x32_bf16 v[114:117], v[134:137], v[166:169], v[114:117]
	v_mfma_f32_16x16x32_bf16 v[122:125], v[142:145], v[166:169], v[122:125]
	v_mfma_f32_16x16x32_bf16 v[118:121], v[134:137], v[174:177], v[118:121]
	v_mfma_f32_16x16x32_bf16 v[126:129], v[142:145], v[174:177], v[126:129]
	v_mfma_f32_16x16x32_bf16 v[54:57], v[134:137], v[182:185], v[54:57]
	v_mfma_f32_16x16x32_bf16 v[70:73], v[142:145], v[182:185], v[70:73]
	v_mfma_f32_16x16x32_bf16 v[50:53], v[134:137], v[190:193], v[50:53]
	v_mfma_f32_16x16x32_bf16 v[66:69], v[142:145], v[190:193], v[66:69]
	s_setprio 0
	s_setprio 1
	v_mfma_f32_16x16x32_bf16 v[106:109], v[146:149], v[162:165], v[106:109]
	v_mfma_f32_16x16x32_bf16 v[42:45], v[154:157], v[162:165], v[42:45]
	v_mfma_f32_16x16x32_bf16 v[110:113], v[146:149], v[170:173], v[110:113]
	v_mfma_f32_16x16x32_bf16 v[46:49], v[154:157], v[170:173], v[46:49]
	v_mfma_f32_16x16x32_bf16 v[30:33], v[146:149], v[178:181], v[30:33]
	v_mfma_f32_16x16x32_bf16 v[14:17], v[154:157], v[178:181], v[14:17]
	v_mfma_f32_16x16x32_bf16 v[26:29], v[146:149], v[186:189], v[26:29]
	v_mfma_f32_16x16x32_bf16 v[10:13], v[154:157], v[186:189], v[10:13]
	v_mfma_f32_16x16x32_bf16 v[106:109], v[150:153], v[166:169], v[106:109]
	v_mfma_f32_16x16x32_bf16 v[42:45], v[158:161], v[166:169], v[42:45]
	v_mfma_f32_16x16x32_bf16 v[110:113], v[150:153], v[174:177], v[110:113]
	v_mfma_f32_16x16x32_bf16 v[46:49], v[158:161], v[174:177], v[46:49]
	v_mfma_f32_16x16x32_bf16 v[30:33], v[150:153], v[182:185], v[30:33]
	v_mfma_f32_16x16x32_bf16 v[14:17], v[158:161], v[182:185], v[14:17]
	v_mfma_f32_16x16x32_bf16 v[26:29], v[150:153], v[190:193], v[26:29]
	s_barrier
	v_mfma_f32_16x16x32_bf16 v[10:13], v[158:161], v[190:193], v[10:13]
	s_setprio 0
	s_add_i32 s4, s6, s74
	v_lshl_add_u64 v[194:195], v[194:195], 0, s[82:83]
	s_mov_b32 m0, s4
	ds_read_b128 v[162:165], v244 offset:49152
	ds_read_b128 v[166:169], v244 offset:50176
	ds_read_b128 v[170:173], v244 offset:51200
	ds_read_b128 v[174:177], v244 offset:52224
	ds_read_b128 v[178:181], v244 offset:53248
	ds_read_b128 v[182:185], v244 offset:54272
	ds_read_b128 v[186:189], v244 offset:55296
	ds_read_b128 v[190:193], v244 offset:56320
	global_load_lds_dwordx4 v[194:195], off
	s_add_i32 m0, s4, 0x2000
	s_add_u32 s4, s66, 0x40080
	v_lshl_add_u64 v[194:195], v[196:197], 0, s[82:83]
	s_addc_u32 s5, s67, 0
	s_add_i32 s6, s7, s74
	global_load_lds_dwordx4 v[194:195], off
	v_lshl_add_u64 v[194:195], s[4:5], 0, v[0:1]
	s_mov_b32 m0, s6
	s_nop 0
	global_load_lds_dwordx4 v[194:195], off
	v_lshl_add_u64 v[194:195], s[4:5], 0, v[224:225]
	s_add_i32 m0, s6, 0x2000
	s_nop 0
	global_load_lds_dwordx4 v[194:195], off
	v_lshl_add_u64 v[194:195], v[198:199], 0, s[82:83]
	s_mov_b32 m0, s94
	s_nop 0
	global_load_lds_dwordx4 v[194:195], off
	v_lshl_add_u64 v[194:195], v[200:201], 0, s[82:83]
	s_mov_b32 m0, s95
	s_nop 0
	global_load_lds_dwordx4 v[194:195], off
	s_waitcnt vmcnt(8)
	s_waitcnt lgkmcnt(0)
	s_barrier
	s_setprio 1
	s_waitcnt lgkmcnt(0)
	v_mfma_f32_16x16x32_bf16 v[38:41], v[130:133], v[162:165], v[38:41]
	v_mfma_f32_16x16x32_bf16 v[62:65], v[138:141], v[162:165], v[62:65]
	v_mfma_f32_16x16x32_bf16 v[34:37], v[130:133], v[170:173], v[34:37]
	v_mfma_f32_16x16x32_bf16 v[58:61], v[138:141], v[170:173], v[58:61]
	v_mfma_f32_16x16x32_bf16 v[102:105], v[130:133], v[178:181], v[102:105]
	v_mfma_f32_16x16x32_bf16 v[98:101], v[138:141], v[178:181], v[98:101]
	v_mfma_f32_16x16x32_bf16 v[94:97], v[130:133], v[186:189], v[94:97]
	v_mfma_f32_16x16x32_bf16 v[90:93], v[138:141], v[186:189], v[90:93]
	v_mfma_f32_16x16x32_bf16 v[38:41], v[134:137], v[166:169], v[38:41]
	v_mfma_f32_16x16x32_bf16 v[62:65], v[142:145], v[166:169], v[62:65]
	v_mfma_f32_16x16x32_bf16 v[34:37], v[134:137], v[174:177], v[34:37]
	v_mfma_f32_16x16x32_bf16 v[58:61], v[142:145], v[174:177], v[58:61]
	v_mfma_f32_16x16x32_bf16 v[102:105], v[134:137], v[182:185], v[102:105]
	v_mfma_f32_16x16x32_bf16 v[98:101], v[142:145], v[182:185], v[98:101]
	v_mfma_f32_16x16x32_bf16 v[94:97], v[134:137], v[190:193], v[94:97]
	v_mfma_f32_16x16x32_bf16 v[90:93], v[142:145], v[190:193], v[90:93]
	s_setprio 0
	s_setprio 1
	v_mfma_f32_16x16x32_bf16 v[22:25], v[146:149], v[162:165], v[22:25]
	v_mfma_f32_16x16x32_bf16 v[6:9], v[154:157], v[162:165], v[6:9]
	v_mfma_f32_16x16x32_bf16 v[18:21], v[146:149], v[170:173], v[18:21]
	v_mfma_f32_16x16x32_bf16 v[2:5], v[154:157], v[170:173], v[2:5]
	v_mfma_f32_16x16x32_bf16 v[86:89], v[146:149], v[178:181], v[86:89]
	v_mfma_f32_16x16x32_bf16 v[82:85], v[154:157], v[178:181], v[82:85]
	v_mfma_f32_16x16x32_bf16 v[78:81], v[146:149], v[186:189], v[78:81]
	v_mfma_f32_16x16x32_bf16 v[74:77], v[154:157], v[186:189], v[74:77]
	v_mfma_f32_16x16x32_bf16 v[22:25], v[150:153], v[166:169], v[22:25]
	v_mfma_f32_16x16x32_bf16 v[6:9], v[158:161], v[166:169], v[6:9]
	v_mfma_f32_16x16x32_bf16 v[18:21], v[150:153], v[174:177], v[18:21]
	v_mfma_f32_16x16x32_bf16 v[2:5], v[158:161], v[174:177], v[2:5]
	v_mfma_f32_16x16x32_bf16 v[86:89], v[150:153], v[182:185], v[86:89]
	v_mfma_f32_16x16x32_bf16 v[82:85], v[158:161], v[182:185], v[82:85]
	v_mfma_f32_16x16x32_bf16 v[78:81], v[150:153], v[190:193], v[78:81]
	s_barrier
	v_mfma_f32_16x16x32_bf16 v[74:77], v[158:161], v[190:193], v[74:77]
	s_setprio 0
	s_add_i32 s73, s73, 2
	s_add_u32 s59, s59, 0x100
	s_addc_u32 s72, s72, 0
	s_cmp_gt_u32 s73, 13
	s_mov_b64 s[42:43], s[38:39]
	s_cbranch_scc0 .LBB0_390
	s_and_b64 vcc, exec, s[50:51]
	s_cbranch_vccz .LBB0_393
	s_barrier

.LBB0_452:
	s_add_i32 s59, s34, 2
	s_add_u32 s4, s30, 0x80
	s_addc_u32 s5, s31, 0
	s_add_i32 s6, 0, 0x10000
	s_cmp_eq_u32 s53, s34
	s_cselect_b32 s35, s27, s5
	s_cselect_b32 s34, s26, s4
	s_cselect_b32 s5, s29, s43
	s_cselect_b32 s4, s28, s42
	s_add_i32 s7, 0, 0x14000
	v_add_u32_e32 v142, s6, v184
	v_add_u32_e32 v168, s7, v184
	ds_read_b128 v[130:133], v142
	ds_read_b128 v[134:137], v142 offset:1024
	ds_read_b128 v[138:141], v142 offset:2048
	ds_read_b128 v[142:145], v142 offset:3072
	ds_read_b128 v[146:149], v168
	ds_read_b128 v[150:153], v168 offset:1024
	ds_read_b128 v[154:157], v168 offset:2048
	ds_read_b128 v[168:171], v168 offset:3072
	v_lshl_add_u64 v[180:181], s[30:31], 0, v[164:165]
	s_add_i32 m0, s38, 0xc000
	ds_read_b128 v[172:175], v187
	ds_read_b128 v[176:179], v187 offset:1024
	ds_read_b128 v[188:191], v187 offset:2048
	ds_read_b128 v[192:195], v187 offset:3072
	ds_read_b128 v[196:199], v187 offset:4096
	ds_read_b128 v[200:203], v187 offset:5120
	ds_read_b128 v[204:207], v187 offset:6144
	ds_read_b128 v[222:225], v187 offset:7168
	global_load_lds_dwordx4 v[180:181], off
	v_lshl_add_u64 v[180:181], s[30:31], 0, v[166:167]
	s_add_i32 m0, s38, 0xe000
	s_nop 0
	global_load_lds_dwordx4 v[180:181], off
	s_waitcnt vmcnt(8)
	s_waitcnt lgkmcnt(0)
	s_barrier
	s_setprio 1
	s_waitcnt lgkmcnt(0)
	v_mfma_f32_16x16x32_bf16 v[126:129], v[130:133], v[172:175], v[126:129]
	v_mfma_f32_16x16x32_bf16 v[122:125], v[138:141], v[172:175], v[122:125]
	v_mfma_f32_16x16x32_bf16 v[110:113], v[130:133], v[188:191], v[110:113]
	v_mfma_f32_16x16x32_bf16 v[106:109], v[138:141], v[188:191], v[106:109]
	v_mfma_f32_16x16x32_bf16 v[98:101], v[130:133], v[196:199], v[98:101]
	v_mfma_f32_16x16x32_bf16 v[90:93], v[138:141], v[196:199], v[90:93]
	v_mfma_f32_16x16x32_bf16 v[82:85], v[130:133], v[204:207], v[82:85]
	v_mfma_f32_16x16x32_bf16 v[74:77], v[138:141], v[204:207], v[74:77]
	v_mfma_f32_16x16x32_bf16 v[126:129], v[134:137], v[176:179], v[126:129]
	v_mfma_f32_16x16x32_bf16 v[122:125], v[142:145], v[176:179], v[122:125]
	v_mfma_f32_16x16x32_bf16 v[110:113], v[134:137], v[192:195], v[110:113]
	v_mfma_f32_16x16x32_bf16 v[106:109], v[142:145], v[192:195], v[106:109]
	v_mfma_f32_16x16x32_bf16 v[98:101], v[134:137], v[200:203], v[98:101]
	v_mfma_f32_16x16x32_bf16 v[90:93], v[142:145], v[200:203], v[90:93]
	v_mfma_f32_16x16x32_bf16 v[82:85], v[134:137], v[222:225], v[82:85]
	v_mfma_f32_16x16x32_bf16 v[74:77], v[142:145], v[222:225], v[74:77]
	s_setprio 0
	s_setprio 1
	v_mfma_f32_16x16x32_bf16 v[118:121], v[146:149], v[172:175], v[118:121]
	v_mfma_f32_16x16x32_bf16 v[114:117], v[154:157], v[172:175], v[114:117]
	v_mfma_f32_16x16x32_bf16 v[102:105], v[146:149], v[188:191], v[102:105]
	v_mfma_f32_16x16x32_bf16 v[94:97], v[154:157], v[188:191], v[94:97]
	v_mfma_f32_16x16x32_bf16 v[86:89], v[146:149], v[196:199], v[86:89]
	v_mfma_f32_16x16x32_bf16 v[78:81], v[154:157], v[196:199], v[78:81]
	v_mfma_f32_16x16x32_bf16 v[70:73], v[146:149], v[204:207], v[70:73]
	v_mfma_f32_16x16x32_bf16 v[66:69], v[154:157], v[204:207], v[66:69]
	v_mfma_f32_16x16x32_bf16 v[118:121], v[150:153], v[176:179], v[118:121]
	v_mfma_f32_16x16x32_bf16 v[114:117], v[168:171], v[176:179], v[114:117]
	v_mfma_f32_16x16x32_bf16 v[102:105], v[150:153], v[192:195], v[102:105]
	v_mfma_f32_16x16x32_bf16 v[94:97], v[168:171], v[192:195], v[94:97]
	v_mfma_f32_16x16x32_bf16 v[86:89], v[150:153], v[200:203], v[86:89]
	v_mfma_f32_16x16x32_bf16 v[78:81], v[168:171], v[200:203], v[78:81]
	v_mfma_f32_16x16x32_bf16 v[70:73], v[150:153], v[222:225], v[70:73]
	s_barrier
	v_mfma_f32_16x16x32_bf16 v[66:69], v[168:171], v[222:225], v[66:69]
	s_setprio 0
	s_add_i32 s6, s6, s37
	v_lshl_add_u64 v[180:181], s[4:5], 0, v[0:1]
	s_mov_b32 m0, s6
	ds_read_b128 v[172:175], v187 offset:16384
	ds_read_b128 v[176:179], v187 offset:17408
	ds_read_b128 v[188:191], v187 offset:18432
	ds_read_b128 v[192:195], v187 offset:19456
	ds_read_b128 v[196:199], v187 offset:20480
	ds_read_b128 v[200:203], v187 offset:21504
	ds_read_b128 v[204:207], v187 offset:22528
	ds_read_b128 v[222:225], v187 offset:23552
	global_load_lds_dwordx4 v[180:181], off
	s_add_i32 m0, s6, 0x2000
	v_lshl_add_u64 v[208:209], s[4:5], 0, v[160:161]
	s_add_u32 s4, s4, s84
	s_addc_u32 s5, s5, 0
	s_add_i32 s6, s7, s37
	global_load_lds_dwordx4 v[208:209], off
	v_lshl_add_u64 v[226:227], s[4:5], 0, v[0:1]
	s_mov_b32 m0, s6
	v_lshl_add_u64 v[228:229], s[4:5], 0, v[160:161]
	global_load_lds_dwordx4 v[226:227], off
	s_add_i32 m0, s6, 0x2000
	v_lshl_add_u64 v[230:231], s[34:35], 0, v[162:163]
	global_load_lds_dwordx4 v[228:229], off
	s_mov_b32 m0, s38
	v_lshl_add_u64 v[232:233], s[34:35], 0, v[158:159]
	global_load_lds_dwordx4 v[230:231], off
	s_mov_b32 m0, s39
	s_nop 0
	global_load_lds_dwordx4 v[232:233], off
	s_waitcnt vmcnt(8)
	s_waitcnt lgkmcnt(0)
	s_barrier
	s_setprio 1
	s_waitcnt lgkmcnt(0)
	v_mfma_f32_16x16x32_bf16 v[62:65], v[130:133], v[172:175], v[62:65]
	v_mfma_f32_16x16x32_bf16 v[58:61], v[138:141], v[172:175], v[58:61]
	v_mfma_f32_16x16x32_bf16 v[46:49], v[130:133], v[188:191], v[46:49]
	v_mfma_f32_16x16x32_bf16 v[42:45], v[138:141], v[188:191], v[42:45]
	v_mfma_f32_16x16x32_bf16 v[34:37], v[130:133], v[196:199], v[34:37]
	v_mfma_f32_16x16x32_bf16 v[26:29], v[138:141], v[196:199], v[26:29]
	v_mfma_f32_16x16x32_bf16 v[18:21], v[130:133], v[204:207], v[18:21]
	v_mfma_f32_16x16x32_bf16 v[10:13], v[138:141], v[204:207], v[10:13]
	v_mfma_f32_16x16x32_bf16 v[62:65], v[134:137], v[176:179], v[62:65]
	v_mfma_f32_16x16x32_bf16 v[58:61], v[142:145], v[176:179], v[58:61]
	v_mfma_f32_16x16x32_bf16 v[46:49], v[134:137], v[192:195], v[46:49]
	v_mfma_f32_16x16x32_bf16 v[42:45], v[142:145], v[192:195], v[42:45]
	v_mfma_f32_16x16x32_bf16 v[34:37], v[134:137], v[200:203], v[34:37]
	v_mfma_f32_16x16x32_bf16 v[26:29], v[142:145], v[200:203], v[26:29]
	v_mfma_f32_16x16x32_bf16 v[18:21], v[134:137], v[222:225], v[18:21]
	v_mfma_f32_16x16x32_bf16 v[10:13], v[142:145], v[222:225], v[10:13]
	s_setprio 0
	s_setprio 1
	v_mfma_f32_16x16x32_bf16 v[54:57], v[146:149], v[172:175], v[54:57]
	v_mfma_f32_16x16x32_bf16 v[50:53], v[154:157], v[172:175], v[50:53]
	v_mfma_f32_16x16x32_bf16 v[38:41], v[146:149], v[188:191], v[38:41]
	v_mfma_f32_16x16x32_bf16 v[30:33], v[154:157], v[188:191], v[30:33]
	v_mfma_f32_16x16x32_bf16 v[22:25], v[146:149], v[196:199], v[22:25]
	v_mfma_f32_16x16x32_bf16 v[14:17], v[154:157], v[196:199], v[14:17]
	v_mfma_f32_16x16x32_bf16 v[6:9], v[146:149], v[204:207], v[6:9]
	v_mfma_f32_16x16x32_bf16 v[2:5], v[154:157], v[204:207], v[2:5]
	v_mfma_f32_16x16x32_bf16 v[54:57], v[150:153], v[176:179], v[54:57]
	v_mfma_f32_16x16x32_bf16 v[50:53], v[168:171], v[176:179], v[50:53]
	v_mfma_f32_16x16x32_bf16 v[38:41], v[150:153], v[192:195], v[38:41]
	v_mfma_f32_16x16x32_bf16 v[30:33], v[168:171], v[192:195], v[30:33]
	v_mfma_f32_16x16x32_bf16 v[22:25], v[150:153], v[200:203], v[22:25]
	v_mfma_f32_16x16x32_bf16 v[14:17], v[168:171], v[200:203], v[14:17]
	v_mfma_f32_16x16x32_bf16 v[6:9], v[150:153], v[222:225], v[6:9]
	s_barrier
	v_mfma_f32_16x16x32_bf16 v[2:5], v[168:171], v[222:225], v[2:5]
	s_setprio 0
	s_add_i32 s6, 0, 0x18000
	s_add_i32 s7, 0, 0x1c000
	v_add_u32_e32 v142, s6, v184
	v_add_u32_e32 v168, s7, v184
	ds_read_b128 v[130:133], v142
	ds_read_b128 v[134:137], v142 offset:1024
	ds_read_b128 v[138:141], v142 offset:2048
	ds_read_b128 v[142:145], v142 offset:3072
	ds_read_b128 v[146:149], v168
	ds_read_b128 v[150:153], v168 offset:1024
	ds_read_b128 v[154:157], v168 offset:2048
	ds_read_b128 v[168:171], v168 offset:3072
	s_add_u32 s4, s34, s84
	s_addc_u32 s5, s35, 0
	s_mov_b32 m0, s45
	v_lshl_add_u64 v[234:235], s[4:5], 0, v[162:163]
	ds_read_b128 v[172:175], v187 offset:32768
	ds_read_b128 v[176:179], v187 offset:33792
	ds_read_b128 v[188:191], v187 offset:34816
	ds_read_b128 v[192:195], v187 offset:35840
	ds_read_b128 v[196:199], v187 offset:36864
	ds_read_b128 v[200:203], v187 offset:37888
	ds_read_b128 v[204:207], v187 offset:38912
	ds_read_b128 v[222:225], v187 offset:39936
	global_load_lds_dwordx4 v[234:235], off
	v_lshl_add_u64 v[234:235], s[4:5], 0, v[158:159]
	s_mov_b32 m0, s46
	s_nop 0
	global_load_lds_dwordx4 v[234:235], off
	s_waitcnt vmcnt(8)
	s_waitcnt lgkmcnt(0)
	s_barrier
	s_setprio 1
	s_waitcnt lgkmcnt(0)
	v_mfma_f32_16x16x32_bf16 v[126:129], v[130:133], v[172:175], v[126:129]
	v_mfma_f32_16x16x32_bf16 v[122:125], v[138:141], v[172:175], v[122:125]
	v_mfma_f32_16x16x32_bf16 v[110:113], v[130:133], v[188:191], v[110:113]
	v_mfma_f32_16x16x32_bf16 v[106:109], v[138:141], v[188:191], v[106:109]
	v_mfma_f32_16x16x32_bf16 v[98:101], v[130:133], v[196:199], v[98:101]
	v_mfma_f32_16x16x32_bf16 v[90:93], v[138:141], v[196:199], v[90:93]
	v_mfma_f32_16x16x32_bf16 v[82:85], v[130:133], v[204:207], v[82:85]
	v_mfma_f32_16x16x32_bf16 v[74:77], v[138:141], v[204:207], v[74:77]
	v_mfma_f32_16x16x32_bf16 v[126:129], v[134:137], v[176:179], v[126:129]
	v_mfma_f32_16x16x32_bf16 v[122:125], v[142:145], v[176:179], v[122:125]
	v_mfma_f32_16x16x32_bf16 v[110:113], v[134:137], v[192:195], v[110:113]
	v_mfma_f32_16x16x32_bf16 v[106:109], v[142:145], v[192:195], v[106:109]
	v_mfma_f32_16x16x32_bf16 v[98:101], v[134:137], v[200:203], v[98:101]
	v_mfma_f32_16x16x32_bf16 v[90:93], v[142:145], v[200:203], v[90:93]
	v_mfma_f32_16x16x32_bf16 v[82:85], v[134:137], v[222:225], v[82:85]
	v_mfma_f32_16x16x32_bf16 v[74:77], v[142:145], v[222:225], v[74:77]
	s_setprio 0
	s_setprio 1
	v_mfma_f32_16x16x32_bf16 v[118:121], v[146:149], v[172:175], v[118:121]
	v_mfma_f32_16x16x32_bf16 v[114:117], v[154:157], v[172:175], v[114:117]
	v_mfma_f32_16x16x32_bf16 v[102:105], v[146:149], v[188:191], v[102:105]
	v_mfma_f32_16x16x32_bf16 v[94:97], v[154:157], v[188:191], v[94:97]
	v_mfma_f32_16x16x32_bf16 v[86:89], v[146:149], v[196:199], v[86:89]
	v_mfma_f32_16x16x32_bf16 v[78:81], v[154:157], v[196:199], v[78:81]
	v_mfma_f32_16x16x32_bf16 v[70:73], v[146:149], v[204:207], v[70:73]
	v_mfma_f32_16x16x32_bf16 v[66:69], v[154:157], v[204:207], v[66:69]
	v_mfma_f32_16x16x32_bf16 v[118:121], v[150:153], v[176:179], v[118:121]
	v_mfma_f32_16x16x32_bf16 v[114:117], v[168:171], v[176:179], v[114:117]
	v_mfma_f32_16x16x32_bf16 v[102:105], v[150:153], v[192:195], v[102:105]
	v_mfma_f32_16x16x32_bf16 v[94:97], v[168:171], v[192:195], v[94:97]
	v_mfma_f32_16x16x32_bf16 v[86:89], v[150:153], v[200:203], v[86:89]
	v_mfma_f32_16x16x32_bf16 v[78:81], v[168:171], v[200:203], v[78:81]
	v_mfma_f32_16x16x32_bf16 v[70:73], v[150:153], v[222:225], v[70:73]
	s_barrier
	v_mfma_f32_16x16x32_bf16 v[66:69], v[168:171], v[222:225], v[66:69]
	s_setprio 0
	s_add_i32 s4, s6, s37
	v_lshl_add_u64 v[180:181], v[180:181], 0, s[82:83]
	s_mov_b32 m0, s4
	ds_read_b128 v[172:175], v187 offset:49152
	ds_read_b128 v[176:179], v187 offset:50176
	ds_read_b128 v[188:191], v187 offset:51200
	ds_read_b128 v[192:195], v187 offset:52224
	ds_read_b128 v[196:199], v187 offset:53248
	ds_read_b128 v[200:203], v187 offset:54272
	ds_read_b128 v[204:207], v187 offset:55296
	ds_read_b128 v[222:225], v187 offset:56320
	global_load_lds_dwordx4 v[180:181], off
	v_lshl_add_u64 v[180:181], v[208:209], 0, s[82:83]
	s_add_i32 m0, s4, 0x2000
	s_add_i32 s4, s7, s37
	global_load_lds_dwordx4 v[180:181], off
	v_lshl_add_u64 v[180:181], v[226:227], 0, s[82:83]
	s_mov_b32 m0, s4
	s_nop 0
	global_load_lds_dwordx4 v[180:181], off
	v_lshl_add_u64 v[180:181], v[228:229], 0, s[82:83]
	s_add_i32 m0, s4, 0x2000
	s_nop 0
	global_load_lds_dwordx4 v[180:181], off
	v_lshl_add_u64 v[180:181], v[230:231], 0, s[82:83]
	s_mov_b32 m0, s51
	s_nop 0
	global_load_lds_dwordx4 v[180:181], off
	v_lshl_add_u64 v[180:181], v[232:233], 0, s[82:83]
	s_mov_b32 m0, s52
	s_nop 0
	global_load_lds_dwordx4 v[180:181], off
	s_waitcnt vmcnt(8)
	s_waitcnt lgkmcnt(0)
	s_barrier
	s_setprio 1
	s_waitcnt lgkmcnt(0)
	v_mfma_f32_16x16x32_bf16 v[62:65], v[130:133], v[172:175], v[62:65]
	v_mfma_f32_16x16x32_bf16 v[58:61], v[138:141], v[172:175], v[58:61]
	v_mfma_f32_16x16x32_bf16 v[46:49], v[130:133], v[188:191], v[46:49]
	v_mfma_f32_16x16x32_bf16 v[42:45], v[138:141], v[188:191], v[42:45]
	v_mfma_f32_16x16x32_bf16 v[34:37], v[130:133], v[196:199], v[34:37]
	v_mfma_f32_16x16x32_bf16 v[26:29], v[138:141], v[196:199], v[26:29]
	v_mfma_f32_16x16x32_bf16 v[18:21], v[130:133], v[204:207], v[18:21]
	v_mfma_f32_16x16x32_bf16 v[10:13], v[138:141], v[204:207], v[10:13]
	v_mfma_f32_16x16x32_bf16 v[62:65], v[134:137], v[176:179], v[62:65]
	v_mfma_f32_16x16x32_bf16 v[58:61], v[142:145], v[176:179], v[58:61]
	v_mfma_f32_16x16x32_bf16 v[46:49], v[134:137], v[192:195], v[46:49]
	v_mfma_f32_16x16x32_bf16 v[42:45], v[142:145], v[192:195], v[42:45]
	v_mfma_f32_16x16x32_bf16 v[34:37], v[134:137], v[200:203], v[34:37]
	v_mfma_f32_16x16x32_bf16 v[26:29], v[142:145], v[200:203], v[26:29]
	v_mfma_f32_16x16x32_bf16 v[18:21], v[134:137], v[222:225], v[18:21]
	v_mfma_f32_16x16x32_bf16 v[10:13], v[142:145], v[222:225], v[10:13]
	s_setprio 0
	s_setprio 1
	v_mfma_f32_16x16x32_bf16 v[54:57], v[146:149], v[172:175], v[54:57]
	v_mfma_f32_16x16x32_bf16 v[50:53], v[154:157], v[172:175], v[50:53]
	v_mfma_f32_16x16x32_bf16 v[38:41], v[146:149], v[188:191], v[38:41]
	v_mfma_f32_16x16x32_bf16 v[30:33], v[154:157], v[188:191], v[30:33]
	v_mfma_f32_16x16x32_bf16 v[22:25], v[146:149], v[196:199], v[22:25]
	v_mfma_f32_16x16x32_bf16 v[14:17], v[154:157], v[196:199], v[14:17]
	v_mfma_f32_16x16x32_bf16 v[6:9], v[146:149], v[204:207], v[6:9]
	v_mfma_f32_16x16x32_bf16 v[2:5], v[154:157], v[204:207], v[2:5]
	v_mfma_f32_16x16x32_bf16 v[54:57], v[150:153], v[176:179], v[54:57]
	v_mfma_f32_16x16x32_bf16 v[50:53], v[168:171], v[176:179], v[50:53]
	v_mfma_f32_16x16x32_bf16 v[38:41], v[150:153], v[192:195], v[38:41]
	v_mfma_f32_16x16x32_bf16 v[30:33], v[168:171], v[192:195], v[30:33]
	v_mfma_f32_16x16x32_bf16 v[22:25], v[150:153], v[200:203], v[22:25]
	v_mfma_f32_16x16x32_bf16 v[14:17], v[168:171], v[200:203], v[14:17]
	v_mfma_f32_16x16x32_bf16 v[6:9], v[150:153], v[222:225], v[6:9]
	s_barrier
	v_mfma_f32_16x16x32_bf16 v[2:5], v[168:171], v[222:225], v[2:5]
	s_setprio 0
	s_add_u32 s30, s30, 0x100
	s_addc_u32 s31, s31, 0
	s_add_u32 s42, s42, 0x100
	s_addc_u32 s43, s43, 0
	s_cmp_ge_u32 s59, s48
	s_mov_b32 s34, s59
	s_cbranch_scc0 .LBB0_452
	s_and_b64 vcc, exec, s[24:25]
	s_cbranch_vccz .LBB0_455
	s_barrier

.LBB0_489:
	s_add_u32 s4, s30, 0xfffc0080
	s_addc_u32 s5, s31, -1
	s_add_i32 s6, 0, 0x10000
	s_cmp_eq_u32 s59, 12
	s_cselect_b32 s37, s25, s5
	s_cselect_b32 s36, s66, s4
	s_cselect_b32 s35, s23, s69
	s_cselect_b32 s34, s67, s68
	s_add_i32 s7, 0, 0x14000
	v_add_u32_e32 v156, s6, v146
	v_add_u32_e32 v172, s7, v146
	ds_read_b128 v[140:143], v156
	ds_read_b128 v[148:151], v156 offset:1024
	ds_read_b128 v[152:155], v156 offset:2048
	ds_read_b128 v[156:159], v156 offset:3072
	ds_read_b128 v[160:163], v172
	ds_read_b128 v[164:167], v172 offset:1024
	ds_read_b128 v[168:171], v172 offset:2048
	ds_read_b128 v[172:175], v172 offset:3072
	v_lshl_add_u64 v[208:209], s[30:31], 0, v[136:137]
	s_add_i32 m0, s43, 0xc000
	ds_read_b128 v[176:179], v147
	ds_read_b128 v[180:183], v147 offset:1024
	ds_read_b128 v[184:187], v147 offset:2048
	ds_read_b128 v[188:191], v147 offset:3072
	ds_read_b128 v[192:195], v147 offset:4096
	ds_read_b128 v[196:199], v147 offset:5120
	ds_read_b128 v[200:203], v147 offset:6144
	ds_read_b128 v[204:207], v147 offset:7168
	global_load_lds_dwordx4 v[208:209], off
	v_lshl_add_u64 v[208:209], s[30:31], 0, v[138:139]
	s_add_i32 m0, s43, 0xe000
	s_nop 0
	global_load_lds_dwordx4 v[208:209], off
	s_waitcnt vmcnt(8)
	s_waitcnt lgkmcnt(0)
	s_barrier
	s_setprio 1
	s_waitcnt lgkmcnt(0)
	v_mfma_f32_16x16x32_bf16 v[126:129], v[140:143], v[176:179], v[126:129]
	v_mfma_f32_16x16x32_bf16 v[122:125], v[152:155], v[176:179], v[122:125]
	v_mfma_f32_16x16x32_bf16 v[118:121], v[140:143], v[184:187], v[118:121]
	v_mfma_f32_16x16x32_bf16 v[110:113], v[152:155], v[184:187], v[110:113]
	v_mfma_f32_16x16x32_bf16 v[102:105], v[140:143], v[192:195], v[102:105]
	v_mfma_f32_16x16x32_bf16 v[94:97], v[152:155], v[192:195], v[94:97]
	v_mfma_f32_16x16x32_bf16 v[86:89], v[140:143], v[200:203], v[86:89]
	v_mfma_f32_16x16x32_bf16 v[78:81], v[152:155], v[200:203], v[78:81]
	v_mfma_f32_16x16x32_bf16 v[126:129], v[148:151], v[180:183], v[126:129]
	v_mfma_f32_16x16x32_bf16 v[122:125], v[156:159], v[180:183], v[122:125]
	v_mfma_f32_16x16x32_bf16 v[118:121], v[148:151], v[188:191], v[118:121]
	v_mfma_f32_16x16x32_bf16 v[110:113], v[156:159], v[188:191], v[110:113]
	v_mfma_f32_16x16x32_bf16 v[102:105], v[148:151], v[196:199], v[102:105]
	v_mfma_f32_16x16x32_bf16 v[94:97], v[156:159], v[196:199], v[94:97]
	v_mfma_f32_16x16x32_bf16 v[86:89], v[148:151], v[204:207], v[86:89]
	v_mfma_f32_16x16x32_bf16 v[78:81], v[156:159], v[204:207], v[78:81]
	s_setprio 0
	s_setprio 1
	v_mfma_f32_16x16x32_bf16 v[114:117], v[160:163], v[176:179], v[114:117]
	v_mfma_f32_16x16x32_bf16 v[106:109], v[168:171], v[176:179], v[106:109]
	v_mfma_f32_16x16x32_bf16 v[98:101], v[160:163], v[184:187], v[98:101]
	v_mfma_f32_16x16x32_bf16 v[90:93], v[168:171], v[184:187], v[90:93]
	v_mfma_f32_16x16x32_bf16 v[82:85], v[160:163], v[192:195], v[82:85]
	v_mfma_f32_16x16x32_bf16 v[74:77], v[168:171], v[192:195], v[74:77]
	v_mfma_f32_16x16x32_bf16 v[70:73], v[160:163], v[200:203], v[70:73]
	v_mfma_f32_16x16x32_bf16 v[66:69], v[168:171], v[200:203], v[66:69]
	v_mfma_f32_16x16x32_bf16 v[114:117], v[164:167], v[180:183], v[114:117]
	v_mfma_f32_16x16x32_bf16 v[106:109], v[172:175], v[180:183], v[106:109]
	v_mfma_f32_16x16x32_bf16 v[98:101], v[164:167], v[188:191], v[98:101]
	v_mfma_f32_16x16x32_bf16 v[90:93], v[172:175], v[188:191], v[90:93]
	v_mfma_f32_16x16x32_bf16 v[82:85], v[164:167], v[196:199], v[82:85]
	v_mfma_f32_16x16x32_bf16 v[74:77], v[172:175], v[196:199], v[74:77]
	v_mfma_f32_16x16x32_bf16 v[70:73], v[164:167], v[204:207], v[70:73]
	s_barrier
	v_mfma_f32_16x16x32_bf16 v[66:69], v[172:175], v[204:207], v[66:69]
	s_setprio 0
	s_add_i32 s4, s6, s38
	v_lshl_add_u64 v[208:209], s[34:35], 0, v[0:1]
	s_mov_b32 m0, s4
	ds_read_b128 v[176:179], v147 offset:16384
	ds_read_b128 v[180:183], v147 offset:17408
	ds_read_b128 v[184:187], v147 offset:18432
	ds_read_b128 v[188:191], v147 offset:19456
	ds_read_b128 v[192:195], v147 offset:20480
	ds_read_b128 v[196:199], v147 offset:21504
	ds_read_b128 v[200:203], v147 offset:22528
	ds_read_b128 v[204:207], v147 offset:23552
	global_load_lds_dwordx4 v[208:209], off
	s_add_i32 m0, s4, 0x2000
	s_add_u32 s4, s34, 0x40000
	v_lshl_add_u64 v[222:223], s[34:35], 0, v[132:133]
	s_addc_u32 s5, s35, 0
	s_add_i32 s6, s7, s38
	global_load_lds_dwordx4 v[222:223], off
	v_lshl_add_u64 v[224:225], s[4:5], 0, v[0:1]
	s_mov_b32 m0, s6
	v_lshl_add_u64 v[226:227], s[36:37], 0, v[130:131]
	global_load_lds_dwordx4 v[224:225], off
	v_lshl_add_u64 v[224:225], s[4:5], 0, v[132:133]
	s_add_i32 m0, s6, 0x2000
	s_nop 0
	global_load_lds_dwordx4 v[224:225], off
	v_lshl_add_u64 v[224:225], s[36:37], 0, v[134:135]
	s_mov_b32 m0, s43
	s_nop 0
	global_load_lds_dwordx4 v[224:225], off
	s_mov_b32 m0, s44
	s_nop 0
	global_load_lds_dwordx4 v[226:227], off
	s_waitcnt vmcnt(8)
	s_waitcnt lgkmcnt(0)
	s_barrier
	s_setprio 1
	s_waitcnt lgkmcnt(0)
	v_mfma_f32_16x16x32_bf16 v[62:65], v[140:143], v[176:179], v[62:65]
	v_mfma_f32_16x16x32_bf16 v[58:61], v[152:155], v[176:179], v[58:61]
	v_mfma_f32_16x16x32_bf16 v[54:57], v[140:143], v[184:187], v[54:57]
	v_mfma_f32_16x16x32_bf16 v[46:49], v[152:155], v[184:187], v[46:49]
	v_mfma_f32_16x16x32_bf16 v[38:41], v[140:143], v[192:195], v[38:41]
	v_mfma_f32_16x16x32_bf16 v[30:33], v[152:155], v[192:195], v[30:33]
	v_mfma_f32_16x16x32_bf16 v[22:25], v[140:143], v[200:203], v[22:25]
	v_mfma_f32_16x16x32_bf16 v[14:17], v[152:155], v[200:203], v[14:17]
	v_mfma_f32_16x16x32_bf16 v[62:65], v[148:151], v[180:183], v[62:65]
	v_mfma_f32_16x16x32_bf16 v[58:61], v[156:159], v[180:183], v[58:61]
	v_mfma_f32_16x16x32_bf16 v[54:57], v[148:151], v[188:191], v[54:57]
	v_mfma_f32_16x16x32_bf16 v[46:49], v[156:159], v[188:191], v[46:49]
	v_mfma_f32_16x16x32_bf16 v[38:41], v[148:151], v[196:199], v[38:41]
	v_mfma_f32_16x16x32_bf16 v[30:33], v[156:159], v[196:199], v[30:33]
	v_mfma_f32_16x16x32_bf16 v[22:25], v[148:151], v[204:207], v[22:25]
	v_mfma_f32_16x16x32_bf16 v[14:17], v[156:159], v[204:207], v[14:17]
	s_setprio 0
	s_setprio 1
	v_mfma_f32_16x16x32_bf16 v[50:53], v[160:163], v[176:179], v[50:53]
	v_mfma_f32_16x16x32_bf16 v[42:45], v[168:171], v[176:179], v[42:45]
	v_mfma_f32_16x16x32_bf16 v[34:37], v[160:163], v[184:187], v[34:37]
	v_mfma_f32_16x16x32_bf16 v[26:29], v[168:171], v[184:187], v[26:29]
	v_mfma_f32_16x16x32_bf16 v[18:21], v[160:163], v[192:195], v[18:21]
	v_mfma_f32_16x16x32_bf16 v[10:13], v[168:171], v[192:195], v[10:13]
	v_mfma_f32_16x16x32_bf16 v[6:9], v[160:163], v[200:203], v[6:9]
	v_mfma_f32_16x16x32_bf16 v[2:5], v[168:171], v[200:203], v[2:5]
	v_mfma_f32_16x16x32_bf16 v[50:53], v[164:167], v[180:183], v[50:53]
	v_mfma_f32_16x16x32_bf16 v[42:45], v[172:175], v[180:183], v[42:45]
	v_mfma_f32_16x16x32_bf16 v[34:37], v[164:167], v[188:191], v[34:37]
	v_mfma_f32_16x16x32_bf16 v[26:29], v[172:175], v[188:191], v[26:29]
	v_mfma_f32_16x16x32_bf16 v[18:21], v[164:167], v[196:199], v[18:21]
	v_mfma_f32_16x16x32_bf16 v[10:13], v[172:175], v[196:199], v[10:13]
	v_mfma_f32_16x16x32_bf16 v[6:9], v[164:167], v[204:207], v[6:9]
	s_barrier
	v_mfma_f32_16x16x32_bf16 v[2:5], v[172:175], v[204:207], v[2:5]
	s_setprio 0
	s_add_i32 s6, 0, 0x18000
	s_add_i32 s7, 0, 0x1c000
	v_add_u32_e32 v156, s6, v146
	v_add_u32_e32 v172, s7, v146
	ds_read_b128 v[140:143], v156
	ds_read_b128 v[148:151], v156 offset:1024
	ds_read_b128 v[152:155], v156 offset:2048
	ds_read_b128 v[156:159], v156 offset:3072
	ds_read_b128 v[160:163], v172
	ds_read_b128 v[164:167], v172 offset:1024
	ds_read_b128 v[168:171], v172 offset:2048
	ds_read_b128 v[172:175], v172 offset:3072
	s_add_u32 s4, s36, 0x40000
	s_addc_u32 s5, s37, 0
	s_mov_b32 m0, s45
	v_lshl_add_u64 v[228:229], s[4:5], 0, v[134:135]
	ds_read_b128 v[176:179], v147 offset:32768
	ds_read_b128 v[180:183], v147 offset:33792
	ds_read_b128 v[184:187], v147 offset:34816
	ds_read_b128 v[188:191], v147 offset:35840
	ds_read_b128 v[192:195], v147 offset:36864
	ds_read_b128 v[196:199], v147 offset:37888
	ds_read_b128 v[200:203], v147 offset:38912
	ds_read_b128 v[204:207], v147 offset:39936
	global_load_lds_dwordx4 v[228:229], off
	v_lshl_add_u64 v[228:229], s[4:5], 0, v[130:131]
	s_mov_b32 m0, s46
	s_nop 0
	global_load_lds_dwordx4 v[228:229], off
	s_waitcnt vmcnt(8)
	s_waitcnt lgkmcnt(0)
	s_barrier
	s_setprio 1
	s_waitcnt lgkmcnt(0)
	v_mfma_f32_16x16x32_bf16 v[126:129], v[140:143], v[176:179], v[126:129]
	v_mfma_f32_16x16x32_bf16 v[122:125], v[152:155], v[176:179], v[122:125]
	v_mfma_f32_16x16x32_bf16 v[118:121], v[140:143], v[184:187], v[118:121]
	v_mfma_f32_16x16x32_bf16 v[110:113], v[152:155], v[184:187], v[110:113]
	v_mfma_f32_16x16x32_bf16 v[102:105], v[140:143], v[192:195], v[102:105]
	v_mfma_f32_16x16x32_bf16 v[94:97], v[152:155], v[192:195], v[94:97]
	v_mfma_f32_16x16x32_bf16 v[86:89], v[140:143], v[200:203], v[86:89]
	v_mfma_f32_16x16x32_bf16 v[78:81], v[152:155], v[200:203], v[78:81]
	v_mfma_f32_16x16x32_bf16 v[126:129], v[148:151], v[180:183], v[126:129]
	v_mfma_f32_16x16x32_bf16 v[122:125], v[156:159], v[180:183], v[122:125]
	v_mfma_f32_16x16x32_bf16 v[118:121], v[148:151], v[188:191], v[118:121]
	v_mfma_f32_16x16x32_bf16 v[110:113], v[156:159], v[188:191], v[110:113]
	v_mfma_f32_16x16x32_bf16 v[102:105], v[148:151], v[196:199], v[102:105]
	v_mfma_f32_16x16x32_bf16 v[94:97], v[156:159], v[196:199], v[94:97]
	v_mfma_f32_16x16x32_bf16 v[86:89], v[148:151], v[204:207], v[86:89]
	v_mfma_f32_16x16x32_bf16 v[78:81], v[156:159], v[204:207], v[78:81]
	s_setprio 0
	s_setprio 1
	v_mfma_f32_16x16x32_bf16 v[114:117], v[160:163], v[176:179], v[114:117]
	v_mfma_f32_16x16x32_bf16 v[106:109], v[168:171], v[176:179], v[106:109]
	v_mfma_f32_16x16x32_bf16 v[98:101], v[160:163], v[184:187], v[98:101]
	v_mfma_f32_16x16x32_bf16 v[90:93], v[168:171], v[184:187], v[90:93]
	v_mfma_f32_16x16x32_bf16 v[82:85], v[160:163], v[192:195], v[82:85]
	v_mfma_f32_16x16x32_bf16 v[74:77], v[168:171], v[192:195], v[74:77]
	v_mfma_f32_16x16x32_bf16 v[70:73], v[160:163], v[200:203], v[70:73]
	v_mfma_f32_16x16x32_bf16 v[66:69], v[168:171], v[200:203], v[66:69]
	v_mfma_f32_16x16x32_bf16 v[114:117], v[164:167], v[180:183], v[114:117]
	v_mfma_f32_16x16x32_bf16 v[106:109], v[172:175], v[180:183], v[106:109]
	v_mfma_f32_16x16x32_bf16 v[98:101], v[164:167], v[188:191], v[98:101]
	v_mfma_f32_16x16x32_bf16 v[90:93], v[172:175], v[188:191], v[90:93]
	v_mfma_f32_16x16x32_bf16 v[82:85], v[164:167], v[196:199], v[82:85]
	v_mfma_f32_16x16x32_bf16 v[74:77], v[172:175], v[196:199], v[74:77]
	v_mfma_f32_16x16x32_bf16 v[70:73], v[164:167], v[204:207], v[70:73]
	s_barrier
	v_mfma_f32_16x16x32_bf16 v[66:69], v[172:175], v[204:207], v[66:69]
	s_setprio 0
	s_add_i32 s4, s6, s38
	v_lshl_add_u64 v[208:209], v[208:209], 0, s[82:83]
	s_mov_b32 m0, s4
	ds_read_b128 v[176:179], v147 offset:49152
	ds_read_b128 v[180:183], v147 offset:50176
	ds_read_b128 v[184:187], v147 offset:51200
	ds_read_b128 v[188:191], v147 offset:52224
	ds_read_b128 v[192:195], v147 offset:53248
	ds_read_b128 v[196:199], v147 offset:54272
	ds_read_b128 v[200:203], v147 offset:55296
	ds_read_b128 v[204:207], v147 offset:56320
	global_load_lds_dwordx4 v[208:209], off
	s_add_i32 m0, s4, 0x2000
	s_add_u32 s4, s34, 0x40080
	v_lshl_add_u64 v[208:209], v[222:223], 0, s[82:83]
	s_addc_u32 s5, s35, 0
	s_add_i32 s6, s7, s38
	global_load_lds_dwordx4 v[208:209], off
	v_lshl_add_u64 v[208:209], s[4:5], 0, v[0:1]
	s_mov_b32 m0, s6
	s_nop 0
	global_load_lds_dwordx4 v[208:209], off
	v_lshl_add_u64 v[208:209], s[4:5], 0, v[132:133]
	s_add_i32 m0, s6, 0x2000
	s_nop 0
	global_load_lds_dwordx4 v[208:209], off
	v_lshl_add_u64 v[208:209], v[224:225], 0, s[82:83]
	s_mov_b32 m0, s49
	s_nop 0
	global_load_lds_dwordx4 v[208:209], off
	v_lshl_add_u64 v[208:209], v[226:227], 0, s[82:83]
	s_mov_b32 m0, s50
	s_nop 0
	global_load_lds_dwordx4 v[208:209], off
	s_waitcnt vmcnt(8)
	s_waitcnt lgkmcnt(0)
	s_barrier
	s_setprio 1
	s_waitcnt lgkmcnt(0)
	v_mfma_f32_16x16x32_bf16 v[62:65], v[140:143], v[176:179], v[62:65]
	v_mfma_f32_16x16x32_bf16 v[58:61], v[152:155], v[176:179], v[58:61]
	v_mfma_f32_16x16x32_bf16 v[54:57], v[140:143], v[184:187], v[54:57]
	v_mfma_f32_16x16x32_bf16 v[46:49], v[152:155], v[184:187], v[46:49]
	v_mfma_f32_16x16x32_bf16 v[38:41], v[140:143], v[192:195], v[38:41]
	v_mfma_f32_16x16x32_bf16 v[30:33], v[152:155], v[192:195], v[30:33]
	v_mfma_f32_16x16x32_bf16 v[22:25], v[140:143], v[200:203], v[22:25]
	v_mfma_f32_16x16x32_bf16 v[14:17], v[152:155], v[200:203], v[14:17]
	v_mfma_f32_16x16x32_bf16 v[62:65], v[148:151], v[180:183], v[62:65]
	v_mfma_f32_16x16x32_bf16 v[58:61], v[156:159], v[180:183], v[58:61]
	v_mfma_f32_16x16x32_bf16 v[54:57], v[148:151], v[188:191], v[54:57]
	v_mfma_f32_16x16x32_bf16 v[46:49], v[156:159], v[188:191], v[46:49]
	v_mfma_f32_16x16x32_bf16 v[38:41], v[148:151], v[196:199], v[38:41]
	v_mfma_f32_16x16x32_bf16 v[30:33], v[156:159], v[196:199], v[30:33]
	v_mfma_f32_16x16x32_bf16 v[22:25], v[148:151], v[204:207], v[22:25]
	v_mfma_f32_16x16x32_bf16 v[14:17], v[156:159], v[204:207], v[14:17]
	s_setprio 0
	s_setprio 1
	v_mfma_f32_16x16x32_bf16 v[50:53], v[160:163], v[176:179], v[50:53]
	v_mfma_f32_16x16x32_bf16 v[42:45], v[168:171], v[176:179], v[42:45]
	v_mfma_f32_16x16x32_bf16 v[34:37], v[160:163], v[184:187], v[34:37]
	v_mfma_f32_16x16x32_bf16 v[26:29], v[168:171], v[184:187], v[26:29]
	v_mfma_f32_16x16x32_bf16 v[18:21], v[160:163], v[192:195], v[18:21]
	v_mfma_f32_16x16x32_bf16 v[10:13], v[168:171], v[192:195], v[10:13]
	v_mfma_f32_16x16x32_bf16 v[6:9], v[160:163], v[200:203], v[6:9]
	v_mfma_f32_16x16x32_bf16 v[2:5], v[168:171], v[200:203], v[2:5]
	v_mfma_f32_16x16x32_bf16 v[50:53], v[164:167], v[180:183], v[50:53]
	v_mfma_f32_16x16x32_bf16 v[42:45], v[172:175], v[180:183], v[42:45]
	v_mfma_f32_16x16x32_bf16 v[34:37], v[164:167], v[188:191], v[34:37]
	v_mfma_f32_16x16x32_bf16 v[26:29], v[172:175], v[188:191], v[26:29]
	v_mfma_f32_16x16x32_bf16 v[18:21], v[164:167], v[196:199], v[18:21]
	v_mfma_f32_16x16x32_bf16 v[10:13], v[172:175], v[196:199], v[10:13]
	v_mfma_f32_16x16x32_bf16 v[6:9], v[164:167], v[204:207], v[6:9]
	s_barrier
	v_mfma_f32_16x16x32_bf16 v[2:5], v[172:175], v[204:207], v[2:5]
	s_setprio 0
	s_add_i32 s59, s59, 2
	s_add_u32 s30, s30, 0x100
	s_addc_u32 s31, s31, 0
	s_add_u32 s68, s68, 0x100
	s_addc_u32 s69, s69, 0
	s_cmp_gt_u32 s59, 13
	s_cbranch_scc0 .LBB0_489
	s_and_b64 vcc, exec, s[20:21]
	s_cbranch_vccz .LBB0_492
	s_barrier
